# phase-2 inner loop: sixteen q elements loaded together at the top of each iteration instead of sixteen serial load-wait-use steps
# speedup vs baseline: 1.0102x; 1.0102x over previous
.LBB0_224:
	s_lshl_b32 s0, s3, 4
	s_or_b32 s0, s0, s72
	s_lshl_b32 s0, s0, 12
	s_mov_b32 s1, 0
	v_lshl_add_u64 v[218:219], v[12:13], 0, s[0:1]
	global_load_ushort v244, v[218:219], off
	v_lshl_add_u64 v[218:219], v[218:219], 0, s[86:87]
	global_load_ushort v245, v[218:219], off
	v_lshl_add_u64 v[218:219], v[218:219], 0, s[86:87]
	global_load_ushort v246, v[218:219], off
	v_lshl_add_u64 v[218:219], v[218:219], 0, s[86:87]
	global_load_ushort v247, v[218:219], off
	v_lshl_add_u64 v[218:219], v[218:219], 0, s[86:87]
	global_load_ushort v248, v[218:219], off
	v_lshl_add_u64 v[218:219], v[218:219], 0, s[86:87]
	global_load_ushort v249, v[218:219], off
	v_lshl_add_u64 v[218:219], v[218:219], 0, s[86:87]
	global_load_ushort v250, v[218:219], off
	v_lshl_add_u64 v[218:219], v[218:219], 0, s[86:87]
	global_load_ushort v251, v[218:219], off
	v_lshl_add_u64 v[218:219], v[218:219], 0, s[86:87]
	global_load_ushort v252, v[218:219], off
	v_lshl_add_u64 v[218:219], v[218:219], 0, s[86:87]
	global_load_ushort v253, v[218:219], off
	v_lshl_add_u64 v[218:219], v[218:219], 0, s[86:87]
	global_load_ushort v237, v[218:219], off
	v_lshl_add_u64 v[218:219], v[218:219], 0, s[86:87]
	global_load_ushort v238, v[218:219], off
	v_lshl_add_u64 v[218:219], v[218:219], 0, s[86:87]
	global_load_ushort v239, v[218:219], off
	v_lshl_add_u64 v[218:219], v[218:219], 0, s[86:87]
	global_load_ushort v240, v[218:219], off
	v_lshl_add_u64 v[218:219], v[218:219], 0, s[86:87]
	global_load_ushort v241, v[218:219], off
	v_lshl_add_u64 v[218:219], v[218:219], 0, s[86:87]
	global_load_ushort v221, v[218:219], off
	s_lshl_b32 s0, s3, 10
	s_add_i32 s0, s0, 0x10000
	v_mov_b32_e32 v14, s0
	ds_read_b128 v[60:63], v14
	ds_read_b128 v[64:67], v14 offset:16
	ds_read_b128 v[68:71], v14 offset:32
	ds_read_b128 v[72:75], v14 offset:48
	s_lshl_b32 s20, s3, 4
	s_waitcnt vmcnt(0) lgkmcnt(3)
	v_fma_f32 v56, v133, v60, v134
	v_fmac_f32_e32 v56, v126, v61
	v_fmac_f32_e32 v56, v127, v62
	v_fmac_f32_e32 v56, v128, v63
	s_waitcnt lgkmcnt(2)
	v_fmac_f32_e32 v56, v129, v64
	v_fmac_f32_e32 v56, v130, v65
	v_fmac_f32_e32 v56, v131, v66
	v_fmac_f32_e32 v56, v132, v67
	s_waitcnt lgkmcnt(1)
	v_fmac_f32_e32 v56, v0, v68
	v_fmac_f32_e32 v56, v1, v69
	v_pk_mul_f32 v[14:15], v[2:3], v[70:71]
	s_or_b32 s50, s20, s72
	v_add_f32_e32 v14, v56, v14
	v_add_f32_e32 v56, v14, v15
	s_waitcnt lgkmcnt(0)
	v_pk_mul_f32 v[14:15], v[4:5], v[72:73]
	s_ashr_i32 s51, s50, 31
	v_add_f32_e32 v14, v56, v14
	v_add_f32_e32 v56, v14, v15
	v_pk_mul_f32 v[14:15], v[6:7], v[74:75]
	s_lshl_b64 s[0:1], s[50:51], 12
	v_add_f32_e32 v14, v56, v14
	v_add_f32_e32 v14, v14, v15
	v_min_f32_e32 v15, 0, v14
	v_mul_f32_e64 v14, |v14|, s65
	v_exp_f32_e32 v14, v14
	s_or_b32 s66, s20, 1
	s_or_b32 s74, s66, s72
	s_ashr_i32 s75, s74, 31
	v_add_f32_e32 v14, 1.0, v14
	v_cmp_gt_f32_e64 s[42:43], s80, v14
	s_or_b32 s73, s20, 2
	s_or_b32 s76, s73, s72
	v_cndmask_b32_e64 v56, 0, 32, s[42:43]
	v_ldexp_f32 v14, v14, v56
	v_log_f32_e32 v14, v14
	s_ashr_i32 s77, s76, 31
	s_or_b32 s68, s20, 3
	s_or_b32 s82, s68, s72
	v_mul_f32_e32 v56, 0x3f317217, v14
	v_fma_f32 v56, v14, s81, -v56
	v_fmac_f32_e32 v56, 0x3377d1cf, v14
	v_fmac_f32_e32 v56, 0x3f317217, v14
	v_cmp_lt_f32_e64 s[44:45], |v14|, s71
	s_ashr_i32 s83, s82, 31
	s_or_b32 s69, s20, 4
	v_cndmask_b32_e64 v14, v14, v56, s[44:45]
	v_cndmask_b32_e64 v56, 0, v236, s[42:43]
	v_sub_f32_e32 v14, v14, v56
	v_sub_f32_e32 v14, v15, v14
	v_fmac_f32_e32 v58, 0x3d800000, v14
	v_lshl_add_u64 v[14:15], v[12:13], 0, s[0:1]
	v_mov_b32_e32 v56, v244
	s_lshl_b32 s0, s66, 6
	s_add_i32 s0, s0, 0x10000
	s_or_b32 s96, s69, s72
	s_ashr_i32 s97, s96, 31
	s_or_b32 s10, s20, 5
	s_or_b32 s8, s10, s72
	s_ashr_i32 s9, s8, 31
	s_or_b32 s11, s20, 6
	s_or_b32 s46, s11, s72
	s_ashr_i32 s47, s46, 31
	s_or_b32 s12, s20, 7
	s_or_b32 s60, s12, s72
	s_ashr_i32 s61, s60, 31
	s_or_b32 s13, s20, 8
	s_or_b32 s62, s13, s72
	s_ashr_i32 s63, s62, 31
	s_or_b32 s14, s20, 9
	s_or_b32 s56, s14, s72
	s_ashr_i32 s57, s56, 31
	s_or_b32 s15, s20, 10
	s_or_b32 s16, s20, 11
	s_or_b32 s6, s16, s72
	s_ashr_i32 s7, s6, 31
	s_or_b32 s17, s20, 12
	s_or_b32 s54, s17, s72
	s_ashr_i32 s55, s54, 31
	s_or_b32 s18, s20, 13
	s_or_b32 s48, s18, s72
	s_ashr_i32 s49, s48, 31
	s_or_b32 s19, s20, 14
	s_or_b32 s20, s20, 15
	s_lshl_b32 s21, s20, 6
	s_add_i32 s21, s21, 0x10000
	v_mul_f32_e32 v161, 0x3fb8aa3b, v58
	v_exp_f32_e32 v161, v161
	v_lshl_add_u32 v179, s73, 9, v112
	v_lshl_add_u32 v181, s68, 9, v113
	v_lshl_add_u32 v192, s12, 9, v117
	s_waitcnt vmcnt(0)
	v_lshlrev_b32_e32 v160, 16, v56
	v_mov_b32_e32 v56, s0
	ds_read_b128 v[60:63], v56
	ds_read_b128 v[64:67], v56 offset:16
	ds_read_b128 v[68:71], v56 offset:32
	ds_read_b128 v[72:75], v56 offset:48
	s_lshl_b64 s[0:1], s[74:75], 12
	s_waitcnt lgkmcnt(3)
	v_fma_f32 v59, v133, v60, v134
	v_fmac_f32_e32 v59, v126, v61
	v_fmac_f32_e32 v59, v127, v62
	v_fmac_f32_e32 v59, v128, v63
	s_waitcnt lgkmcnt(2)
	v_fmac_f32_e32 v59, v129, v64
	v_fmac_f32_e32 v59, v130, v65
	v_fmac_f32_e32 v59, v131, v66
	v_fmac_f32_e32 v59, v132, v67
	s_waitcnt lgkmcnt(1)
	v_fmac_f32_e32 v59, v0, v68
	v_fmac_f32_e32 v59, v1, v69
	v_pk_mul_f32 v[56:57], v[2:3], v[70:71]
	v_mul_f32_e32 v160, 0x3d800000, v160
	v_add_f32_e32 v56, v59, v56
	v_add_f32_e32 v59, v56, v57
	s_waitcnt lgkmcnt(0)
	v_pk_mul_f32 v[56:57], v[4:5], v[72:73]
	v_mul_f32_e32 v160, v160, v161
	v_add_f32_e32 v56, v59, v56
	v_add_f32_e32 v59, v56, v57
	v_pk_mul_f32 v[56:57], v[6:7], v[74:75]
	s_nop 0
	v_add_f32_e32 v56, v59, v56
	v_add_f32_e32 v56, v56, v57
	v_min_f32_e32 v57, 0, v56
	v_mul_f32_e64 v56, |v56|, s65
	v_exp_f32_e32 v56, v56
	s_nop 0
	v_add_f32_e32 v56, 1.0, v56
	v_cmp_gt_f32_e64 s[42:43], s80, v56
	s_nop 1
	v_cndmask_b32_e64 v59, 0, 32, s[42:43]
	v_ldexp_f32 v56, v56, v59
	v_log_f32_e32 v56, v56
	s_nop 0
	v_mul_f32_e32 v59, 0x3f317217, v56
	v_fma_f32 v59, v56, s81, -v59
	v_fmac_f32_e32 v59, 0x3377d1cf, v56
	v_fmac_f32_e32 v59, 0x3f317217, v56
	v_cmp_lt_f32_e64 s[44:45], |v56|, s71
	s_nop 1
	v_cndmask_b32_e64 v56, v56, v59, s[44:45]
	v_cndmask_b32_e64 v59, 0, v236, s[42:43]
	v_sub_f32_e32 v56, v56, v59
	v_sub_f32_e32 v56, v57, v56
	v_fmamk_f32 v59, v56, 0x3d800000, v58
	v_lshl_add_u64 v[56:57], v[12:13], 0, s[0:1]
	v_mov_b32_e32 v60, v245
	s_lshl_b32 s0, s73, 6
	s_add_i32 s0, s0, 0x10000
	v_mov_b32_e32 v72, s0
	s_lshl_b64 s[0:1], s[76:77], 12
	v_mul_f32_e32 v58, 0xbfb8aa3b, v58
	v_exp_f32_e32 v58, v58
	s_waitcnt vmcnt(0)
	v_lshlrev_b32_e32 v88, 16, v60
	ds_read_b128 v[60:63], v72
	ds_read_b128 v[64:67], v72 offset:16
	ds_read_b128 v[68:71], v72 offset:32
	ds_read_b128 v[72:75], v72 offset:48
	s_waitcnt lgkmcnt(3)
	v_fma_f32 v76, v133, v60, v134
	v_fmac_f32_e32 v76, v126, v61
	v_fmac_f32_e32 v76, v127, v62
	v_fmac_f32_e32 v76, v128, v63
	s_waitcnt lgkmcnt(2)
	v_fmac_f32_e32 v76, v129, v64
	v_fmac_f32_e32 v76, v130, v65
	v_fmac_f32_e32 v76, v131, v66
	v_fmac_f32_e32 v76, v132, v67
	s_waitcnt lgkmcnt(1)
	v_fmac_f32_e32 v76, v0, v68
	v_fmac_f32_e32 v76, v1, v69
	v_pk_mul_f32 v[60:61], v[2:3], v[70:71]
	s_nop 0
	v_add_f32_e32 v60, v76, v60
	v_add_f32_e32 v62, v60, v61
	s_waitcnt lgkmcnt(0)
	v_pk_mul_f32 v[60:61], v[4:5], v[72:73]
	s_nop 0
	v_add_f32_e32 v60, v62, v60
	v_add_f32_e32 v62, v60, v61
	v_pk_mul_f32 v[60:61], v[6:7], v[74:75]
	s_nop 0
	v_add_f32_e32 v60, v62, v60
	v_add_f32_e32 v60, v60, v61
	v_min_f32_e32 v61, 0, v60
	v_mul_f32_e64 v60, |v60|, s65
	v_exp_f32_e32 v60, v60
	s_nop 0
	v_add_f32_e32 v60, 1.0, v60
	v_cmp_gt_f32_e64 s[42:43], s80, v60
	s_nop 1
	v_cndmask_b32_e64 v62, 0, 32, s[42:43]
	v_ldexp_f32 v60, v60, v62
	v_log_f32_e32 v60, v60
	s_nop 0
	v_mul_f32_e32 v62, 0x3f317217, v60
	v_fma_f32 v62, v60, s81, -v62
	v_fmac_f32_e32 v62, 0x3377d1cf, v60
	v_fmac_f32_e32 v62, 0x3f317217, v60
	v_cmp_lt_f32_e64 s[44:45], |v60|, s71
	s_nop 1
	v_cndmask_b32_e64 v60, v60, v62, s[44:45]
	v_cndmask_b32_e64 v62, 0, v236, s[42:43]
	v_sub_f32_e32 v60, v60, v62
	v_sub_f32_e32 v60, v61, v60
	v_fmamk_f32 v89, v60, 0x3d800000, v59
	v_lshl_add_u64 v[60:61], v[12:13], 0, s[0:1]
	v_mov_b32_e32 v62, v246
	s_lshl_b32 s0, s68, 6
	s_add_i32 s0, s0, 0x10000
	v_mov_b32_e32 v74, s0
	s_lshl_b64 s[0:1], s[82:83], 12
	s_waitcnt vmcnt(0)
	v_lshlrev_b32_e32 v90, 16, v62
	ds_read_b128 v[62:65], v74
	ds_read_b128 v[66:69], v74 offset:16
	ds_read_b128 v[70:73], v74 offset:32
	ds_read_b128 v[74:77], v74 offset:48
	s_waitcnt lgkmcnt(3)
	v_fma_f32 v78, v133, v62, v134
	v_fmac_f32_e32 v78, v126, v63
	v_fmac_f32_e32 v78, v127, v64
	v_fmac_f32_e32 v78, v128, v65
	s_waitcnt lgkmcnt(2)
	v_fmac_f32_e32 v78, v129, v66
	v_fmac_f32_e32 v78, v130, v67
	v_fmac_f32_e32 v78, v131, v68
	v_fmac_f32_e32 v78, v132, v69
	s_waitcnt lgkmcnt(1)
	v_fmac_f32_e32 v78, v0, v70
	v_fmac_f32_e32 v78, v1, v71
	v_pk_mul_f32 v[62:63], v[2:3], v[72:73]
	s_nop 0
	v_add_f32_e32 v62, v78, v62
	v_add_f32_e32 v64, v62, v63
	s_waitcnt lgkmcnt(0)
	v_pk_mul_f32 v[62:63], v[4:5], v[74:75]
	s_nop 0
	v_add_f32_e32 v62, v64, v62
	v_add_f32_e32 v64, v62, v63
	v_pk_mul_f32 v[62:63], v[6:7], v[76:77]
	s_nop 0
	v_add_f32_e32 v62, v64, v62
	v_add_f32_e32 v62, v62, v63
	v_min_f32_e32 v63, 0, v62
	v_mul_f32_e64 v62, |v62|, s65
	v_exp_f32_e32 v62, v62
	s_nop 0
	v_add_f32_e32 v62, 1.0, v62
	v_cmp_gt_f32_e64 s[42:43], s80, v62
	s_nop 1
	v_cndmask_b32_e64 v64, 0, 32, s[42:43]
	v_ldexp_f32 v62, v62, v64
	v_log_f32_e32 v62, v62
	s_nop 0
	v_mul_f32_e32 v64, 0x3f317217, v62
	v_fma_f32 v64, v62, s81, -v64
	v_fmac_f32_e32 v64, 0x3377d1cf, v62
	v_fmac_f32_e32 v64, 0x3f317217, v62
	v_cmp_lt_f32_e64 s[44:45], |v62|, s71
	s_nop 1
	v_cndmask_b32_e64 v62, v62, v64, s[44:45]
	v_cndmask_b32_e64 v64, 0, v236, s[42:43]
	v_sub_f32_e32 v62, v62, v64
	v_sub_f32_e32 v62, v63, v62
	v_fmamk_f32 v91, v62, 0x3d800000, v89
	v_lshl_add_u64 v[62:63], v[12:13], 0, s[0:1]
	v_mov_b32_e32 v64, v247
	s_lshl_b32 s0, s69, 6
	s_add_i32 s0, s0, 0x10000
	v_mov_b32_e32 v76, s0
	s_lshl_b64 s[0:1], s[96:97], 12
	s_waitcnt vmcnt(0)
	v_lshlrev_b32_e32 v136, 16, v64
	ds_read_b128 v[64:67], v76
	ds_read_b128 v[68:71], v76 offset:16
	ds_read_b128 v[72:75], v76 offset:32
	ds_read_b128 v[76:79], v76 offset:48
	s_waitcnt lgkmcnt(3)
	v_fma_f32 v80, v133, v64, v134
	v_fmac_f32_e32 v80, v126, v65
	v_fmac_f32_e32 v80, v127, v66
	v_fmac_f32_e32 v80, v128, v67
	s_waitcnt lgkmcnt(2)
	v_fmac_f32_e32 v80, v129, v68
	v_fmac_f32_e32 v80, v130, v69
	v_fmac_f32_e32 v80, v131, v70
	v_fmac_f32_e32 v80, v132, v71
	s_waitcnt lgkmcnt(1)
	v_fmac_f32_e32 v80, v0, v72
	v_fmac_f32_e32 v80, v1, v73
	v_pk_mul_f32 v[64:65], v[2:3], v[74:75]
	s_nop 0
	v_add_f32_e32 v64, v80, v64
	v_add_f32_e32 v66, v64, v65
	s_waitcnt lgkmcnt(0)
	v_pk_mul_f32 v[64:65], v[4:5], v[76:77]
	s_nop 0
	v_add_f32_e32 v64, v66, v64
	v_add_f32_e32 v66, v64, v65
	v_pk_mul_f32 v[64:65], v[6:7], v[78:79]
	s_nop 0
	v_add_f32_e32 v64, v66, v64
	v_add_f32_e32 v64, v64, v65
	v_min_f32_e32 v65, 0, v64
	v_mul_f32_e64 v64, |v64|, s65
	v_exp_f32_e32 v64, v64
	s_nop 0
	v_add_f32_e32 v64, 1.0, v64
	v_cmp_gt_f32_e64 s[42:43], s80, v64
	s_nop 1
	v_cndmask_b32_e64 v66, 0, 32, s[42:43]
	v_ldexp_f32 v64, v64, v66
	v_log_f32_e32 v64, v64
	s_nop 0
	v_mul_f32_e32 v66, 0x3f317217, v64
	v_fma_f32 v66, v64, s81, -v66
	v_fmac_f32_e32 v66, 0x3377d1cf, v64
	v_fmac_f32_e32 v66, 0x3f317217, v64
	v_cmp_lt_f32_e64 s[44:45], |v64|, s71
	s_nop 1
	v_cndmask_b32_e64 v64, v64, v66, s[44:45]
	v_cndmask_b32_e64 v66, 0, v236, s[42:43]
	v_sub_f32_e32 v64, v64, v66
	v_sub_f32_e32 v64, v65, v64
	v_fmamk_f32 v137, v64, 0x3d800000, v91
	v_lshl_add_u64 v[64:65], v[12:13], 0, s[0:1]
	v_mov_b32_e32 v66, v248
	s_lshl_b32 s0, s10, 6
	s_add_i32 s0, s0, 0x10000
	v_mov_b32_e32 v78, s0
	s_lshl_b64 s[0:1], s[8:9], 12
	s_lshl_b64 s[8:9], s[8:9], 11
	s_waitcnt vmcnt(0)
	v_lshlrev_b32_e32 v138, 16, v66
	ds_read_b128 v[66:69], v78
	ds_read_b128 v[70:73], v78 offset:16
	ds_read_b128 v[74:77], v78 offset:32
	ds_read_b128 v[78:81], v78 offset:48
	s_waitcnt lgkmcnt(3)
	v_fma_f32 v82, v133, v66, v134
	v_fmac_f32_e32 v82, v126, v67
	v_fmac_f32_e32 v82, v127, v68
	v_fmac_f32_e32 v82, v128, v69
	s_waitcnt lgkmcnt(2)
	v_fmac_f32_e32 v82, v129, v70
	v_fmac_f32_e32 v82, v130, v71
	v_fmac_f32_e32 v82, v131, v72
	v_fmac_f32_e32 v82, v132, v73
	s_waitcnt lgkmcnt(1)
	v_fmac_f32_e32 v82, v0, v74
	v_fmac_f32_e32 v82, v1, v75
	v_pk_mul_f32 v[66:67], v[2:3], v[76:77]
	s_nop 0
	v_add_f32_e32 v66, v82, v66
	v_add_f32_e32 v68, v66, v67
	s_waitcnt lgkmcnt(0)
	v_pk_mul_f32 v[66:67], v[4:5], v[78:79]
	s_nop 0
	v_add_f32_e32 v66, v68, v66
	v_add_f32_e32 v68, v66, v67
	v_pk_mul_f32 v[66:67], v[6:7], v[80:81]
	s_nop 0
	v_add_f32_e32 v66, v68, v66
	v_add_f32_e32 v66, v66, v67
	v_min_f32_e32 v67, 0, v66
	v_mul_f32_e64 v66, |v66|, s65
	v_exp_f32_e32 v66, v66
	s_nop 0
	v_add_f32_e32 v66, 1.0, v66
	v_cmp_gt_f32_e64 s[42:43], s80, v66
	s_nop 1
	v_cndmask_b32_e64 v68, 0, 32, s[42:43]
	v_ldexp_f32 v66, v66, v68
	v_log_f32_e32 v66, v66
	s_nop 0
	v_mul_f32_e32 v68, 0x3f317217, v66
	v_fma_f32 v68, v66, s81, -v68
	v_fmac_f32_e32 v68, 0x3377d1cf, v66
	v_fmac_f32_e32 v68, 0x3f317217, v66
	v_cmp_lt_f32_e64 s[44:45], |v66|, s71
	s_nop 1
	v_cndmask_b32_e64 v66, v66, v68, s[44:45]
	v_cndmask_b32_e64 v68, 0, v236, s[42:43]
	v_sub_f32_e32 v66, v66, v68
	v_sub_f32_e32 v66, v67, v66
	v_fmamk_f32 v139, v66, 0x3d800000, v137
	v_lshl_add_u64 v[66:67], v[12:13], 0, s[0:1]
	v_mov_b32_e32 v68, v249
	s_lshl_b32 s0, s11, 6
	s_add_i32 s0, s0, 0x10000
	v_mov_b32_e32 v80, s0
	s_lshl_b64 s[0:1], s[46:47], 12
	s_waitcnt vmcnt(0)
	v_lshlrev_b32_e32 v140, 16, v68
	ds_read_b128 v[68:71], v80
	ds_read_b128 v[72:75], v80 offset:16
	ds_read_b128 v[76:79], v80 offset:32
	ds_read_b128 v[80:83], v80 offset:48
	s_waitcnt lgkmcnt(3)
	v_fma_f32 v84, v133, v68, v134
	v_fmac_f32_e32 v84, v126, v69
	v_fmac_f32_e32 v84, v127, v70
	v_fmac_f32_e32 v84, v128, v71
	s_waitcnt lgkmcnt(2)
	v_fmac_f32_e32 v84, v129, v72
	v_fmac_f32_e32 v84, v130, v73
	v_fmac_f32_e32 v84, v131, v74
	v_fmac_f32_e32 v84, v132, v75
	s_waitcnt lgkmcnt(1)
	v_fmac_f32_e32 v84, v0, v76
	v_fmac_f32_e32 v84, v1, v77
	v_pk_mul_f32 v[68:69], v[2:3], v[78:79]
	s_nop 0
	v_add_f32_e32 v68, v84, v68
	v_add_f32_e32 v70, v68, v69
	s_waitcnt lgkmcnt(0)
	v_pk_mul_f32 v[68:69], v[4:5], v[80:81]
	s_nop 0
	v_add_f32_e32 v68, v70, v68
	v_add_f32_e32 v70, v68, v69
	v_pk_mul_f32 v[68:69], v[6:7], v[82:83]
	s_nop 0
	v_add_f32_e32 v68, v70, v68
	v_add_f32_e32 v68, v68, v69
	v_min_f32_e32 v69, 0, v68
	v_mul_f32_e64 v68, |v68|, s65
	v_exp_f32_e32 v68, v68
	s_nop 0
	v_add_f32_e32 v68, 1.0, v68
	v_cmp_gt_f32_e64 s[42:43], s80, v68
	s_nop 1
	v_cndmask_b32_e64 v70, 0, 32, s[42:43]
	v_ldexp_f32 v68, v68, v70
	v_log_f32_e32 v68, v68
	s_nop 0
	v_mul_f32_e32 v70, 0x3f317217, v68
	v_fma_f32 v70, v68, s81, -v70
	v_fmac_f32_e32 v70, 0x3377d1cf, v68
	v_fmac_f32_e32 v70, 0x3f317217, v68
	v_cmp_lt_f32_e64 s[44:45], |v68|, s71
	s_nop 1
	v_cndmask_b32_e64 v68, v68, v70, s[44:45]
	v_cndmask_b32_e64 v70, 0, v236, s[42:43]
	v_sub_f32_e32 v68, v68, v70
	v_sub_f32_e32 v68, v69, v68
	v_fmamk_f32 v141, v68, 0x3d800000, v139
	v_lshl_add_u64 v[68:69], v[12:13], 0, s[0:1]
	v_mov_b32_e32 v70, v250
	s_lshl_b32 s0, s12, 6
	s_add_i32 s0, s0, 0x10000
	v_mov_b32_e32 v82, s0
	s_lshl_b64 s[0:1], s[60:61], 12
	s_waitcnt vmcnt(0)
	v_lshlrev_b32_e32 v142, 16, v70
	ds_read_b128 v[70:73], v82
	ds_read_b128 v[74:77], v82 offset:16
	ds_read_b128 v[78:81], v82 offset:32
	ds_read_b128 v[82:85], v82 offset:48
	s_waitcnt lgkmcnt(3)
	v_fma_f32 v86, v133, v70, v134
	v_fmac_f32_e32 v86, v126, v71
	v_fmac_f32_e32 v86, v127, v72
	v_fmac_f32_e32 v86, v128, v73
	s_waitcnt lgkmcnt(2)
	v_fmac_f32_e32 v86, v129, v74
	v_fmac_f32_e32 v86, v130, v75
	v_fmac_f32_e32 v86, v131, v76
	v_fmac_f32_e32 v86, v132, v77
	s_waitcnt lgkmcnt(1)
	v_fmac_f32_e32 v86, v0, v78
	v_fmac_f32_e32 v86, v1, v79
	v_pk_mul_f32 v[70:71], v[2:3], v[80:81]
	s_nop 0
	v_add_f32_e32 v70, v86, v70
	v_add_f32_e32 v72, v70, v71
	s_waitcnt lgkmcnt(0)
	v_pk_mul_f32 v[70:71], v[4:5], v[82:83]
	s_nop 0
	v_add_f32_e32 v70, v72, v70
	v_add_f32_e32 v72, v70, v71
	v_pk_mul_f32 v[70:71], v[6:7], v[84:85]
	s_nop 0
	v_add_f32_e32 v70, v72, v70
	v_add_f32_e32 v70, v70, v71
	v_min_f32_e32 v71, 0, v70
	v_mul_f32_e64 v70, |v70|, s65
	v_exp_f32_e32 v70, v70
	s_nop 0
	v_add_f32_e32 v70, 1.0, v70
	v_cmp_gt_f32_e64 s[42:43], s80, v70
	s_nop 1
	v_cndmask_b32_e64 v72, 0, 32, s[42:43]
	v_ldexp_f32 v70, v70, v72
	v_log_f32_e32 v70, v70
	s_nop 0
	v_mul_f32_e32 v72, 0x3f317217, v70
	v_fma_f32 v72, v70, s81, -v72
	v_fmac_f32_e32 v72, 0x3377d1cf, v70
	v_fmac_f32_e32 v72, 0x3f317217, v70
	v_cmp_lt_f32_e64 s[44:45], |v70|, s71
	s_nop 1
	v_cndmask_b32_e64 v70, v70, v72, s[44:45]
	v_cndmask_b32_e64 v72, 0, v236, s[42:43]
	v_sub_f32_e32 v70, v70, v72
	v_sub_f32_e32 v70, v71, v70
	v_fmamk_f32 v143, v70, 0x3d800000, v141
	v_lshl_add_u64 v[70:71], v[12:13], 0, s[0:1]
	v_mov_b32_e32 v72, v251
	s_lshl_b32 s0, s13, 6
	s_add_i32 s0, s0, 0x10000
	v_mov_b32_e32 v84, s0
	s_lshl_b64 s[0:1], s[62:63], 12
	s_waitcnt vmcnt(0)
	v_lshlrev_b32_e32 v144, 16, v72
	ds_read_b128 v[72:75], v84
	ds_read_b128 v[76:79], v84 offset:16
	ds_read_b128 v[80:83], v84 offset:32
	ds_read_b128 v[84:87], v84 offset:48
	s_waitcnt lgkmcnt(3)
	v_fma_f32 v135, v133, v72, v134
	v_fmac_f32_e32 v135, v126, v73
	v_fmac_f32_e32 v135, v127, v74
	v_fmac_f32_e32 v135, v128, v75
	s_waitcnt lgkmcnt(2)
	v_fmac_f32_e32 v135, v129, v76
	v_fmac_f32_e32 v135, v130, v77
	v_fmac_f32_e32 v135, v131, v78
	v_fmac_f32_e32 v135, v132, v79
	s_waitcnt lgkmcnt(1)
	v_fmac_f32_e32 v135, v0, v80
	v_fmac_f32_e32 v135, v1, v81
	v_pk_mul_f32 v[72:73], v[2:3], v[82:83]
	s_nop 0
	v_add_f32_e32 v72, v135, v72
	v_add_f32_e32 v74, v72, v73
	s_waitcnt lgkmcnt(0)
	v_pk_mul_f32 v[72:73], v[4:5], v[84:85]
	s_nop 0
	v_add_f32_e32 v72, v74, v72
	v_add_f32_e32 v74, v72, v73
	v_pk_mul_f32 v[72:73], v[6:7], v[86:87]
	s_nop 0
	v_add_f32_e32 v72, v74, v72
	v_add_f32_e32 v72, v72, v73
	v_min_f32_e32 v73, 0, v72
	v_mul_f32_e64 v72, |v72|, s65
	v_exp_f32_e32 v72, v72
	s_nop 0
	v_add_f32_e32 v72, 1.0, v72
	v_cmp_gt_f32_e64 s[42:43], s80, v72
	s_nop 1
	v_cndmask_b32_e64 v74, 0, 32, s[42:43]
	v_ldexp_f32 v72, v72, v74
	v_log_f32_e32 v72, v72
	s_nop 0
	v_mul_f32_e32 v74, 0x3f317217, v72
	v_fma_f32 v74, v72, s81, -v74
	v_fmac_f32_e32 v74, 0x3377d1cf, v72
	v_fmac_f32_e32 v74, 0x3f317217, v72
	v_cmp_lt_f32_e64 s[44:45], |v72|, s71
	s_nop 1
	v_cndmask_b32_e64 v72, v72, v74, s[44:45]
	v_cndmask_b32_e64 v74, 0, v236, s[42:43]
	v_sub_f32_e32 v72, v72, v74
	v_sub_f32_e32 v72, v73, v72
	v_fmamk_f32 v145, v72, 0x3d800000, v143
	v_lshl_add_u64 v[72:73], v[12:13], 0, s[0:1]
	v_mov_b32_e32 v74, v252
	s_lshl_b32 s0, s14, 6
	s_add_i32 s0, s0, 0x10000
	v_mov_b32_e32 v86, s0
	s_lshl_b64 s[0:1], s[56:57], 12
	s_waitcnt vmcnt(0)
	v_lshlrev_b32_e32 v146, 16, v74
	ds_read_b128 v[74:77], v86
	ds_read_b128 v[78:81], v86 offset:16
	ds_read_b128 v[82:85], v86 offset:32
	ds_read_b128 v[148:151], v86 offset:48
	s_waitcnt lgkmcnt(3)
	v_fma_f32 v86, v133, v74, v134
	v_fmac_f32_e32 v86, v126, v75
	v_fmac_f32_e32 v86, v127, v76
	v_fmac_f32_e32 v86, v128, v77
	s_waitcnt lgkmcnt(2)
	v_fmac_f32_e32 v86, v129, v78
	v_fmac_f32_e32 v86, v130, v79
	v_fmac_f32_e32 v86, v131, v80
	v_fmac_f32_e32 v86, v132, v81
	s_waitcnt lgkmcnt(1)
	v_fmac_f32_e32 v86, v0, v82
	v_fmac_f32_e32 v86, v1, v83
	v_pk_mul_f32 v[74:75], v[2:3], v[84:85]
	s_nop 0
	v_add_f32_e32 v74, v86, v74
	v_add_f32_e32 v76, v74, v75
	s_waitcnt lgkmcnt(0)
	v_pk_mul_f32 v[74:75], v[4:5], v[148:149]
	s_nop 0
	v_add_f32_e32 v74, v76, v74
	v_add_f32_e32 v76, v74, v75
	v_pk_mul_f32 v[74:75], v[6:7], v[150:151]
	s_nop 0
	v_add_f32_e32 v74, v76, v74
	v_add_f32_e32 v74, v74, v75
	v_min_f32_e32 v75, 0, v74
	v_mul_f32_e64 v74, |v74|, s65
	v_exp_f32_e32 v74, v74
	s_nop 0
	v_add_f32_e32 v74, 1.0, v74
	v_cmp_gt_f32_e64 s[42:43], s80, v74
	s_nop 1
	v_cndmask_b32_e64 v76, 0, 32, s[42:43]
	v_ldexp_f32 v74, v74, v76
	v_log_f32_e32 v74, v74
	s_nop 0
	v_mul_f32_e32 v76, 0x3f317217, v74
	v_fma_f32 v76, v74, s81, -v76
	v_fmac_f32_e32 v76, 0x3377d1cf, v74
	v_fmac_f32_e32 v76, 0x3f317217, v74
	v_cmp_lt_f32_e64 s[44:45], |v74|, s71
	s_nop 1
	v_cndmask_b32_e64 v74, v74, v76, s[44:45]
	v_cndmask_b32_e64 v76, 0, v236, s[42:43]
	v_sub_f32_e32 v74, v74, v76
	v_sub_f32_e32 v74, v75, v74
	v_fmamk_f32 v147, v74, 0x3d800000, v145
	v_lshl_add_u64 v[74:75], v[12:13], 0, s[0:1]
	v_mov_b32_e32 v76, v253
	s_lshl_b32 s0, s15, 6
	s_add_i32 s0, s0, 0x10000
	v_mov_b32_e32 v135, s0
	s_or_b32 s0, s15, s72
	s_ashr_i32 s1, s0, 31
	s_lshl_b64 s[4:5], s[0:1], 12
	v_cvt_pk_bf16_f32 v160, v160, s0
	s_waitcnt vmcnt(0)
	v_lshlrev_b32_e32 v148, 16, v76
	ds_read_b128 v[76:79], v135
	ds_read_b128 v[80:83], v135 offset:16
	ds_read_b128 v[84:87], v135 offset:32
	ds_read_b128 v[150:153], v135 offset:48
	s_waitcnt lgkmcnt(3)
	v_fma_f32 v135, v133, v76, v134
	v_fmac_f32_e32 v135, v126, v77
	v_fmac_f32_e32 v135, v127, v78
	v_fmac_f32_e32 v135, v128, v79
	s_waitcnt lgkmcnt(2)
	v_fmac_f32_e32 v135, v129, v80
	v_fmac_f32_e32 v135, v130, v81
	v_fmac_f32_e32 v135, v131, v82
	v_fmac_f32_e32 v135, v132, v83
	s_waitcnt lgkmcnt(1)
	v_fmac_f32_e32 v135, v0, v84
	v_fmac_f32_e32 v135, v1, v85
	v_pk_mul_f32 v[76:77], v[2:3], v[86:87]
	s_nop 0
	v_add_f32_e32 v76, v135, v76
	v_add_f32_e32 v78, v76, v77
	s_waitcnt lgkmcnt(0)
	v_pk_mul_f32 v[76:77], v[4:5], v[150:151]
	s_nop 0
	v_add_f32_e32 v76, v78, v76
	v_add_f32_e32 v78, v76, v77
	v_pk_mul_f32 v[76:77], v[6:7], v[152:153]
	s_nop 0
	v_add_f32_e32 v76, v78, v76
	v_add_f32_e32 v76, v76, v77
	v_min_f32_e32 v77, 0, v76
	v_mul_f32_e64 v76, |v76|, s65
	v_exp_f32_e32 v76, v76
	s_nop 0
	v_add_f32_e32 v76, 1.0, v76
	v_cmp_gt_f32_e64 s[42:43], s80, v76
	s_nop 1
	v_cndmask_b32_e64 v78, 0, 32, s[42:43]
	v_ldexp_f32 v76, v76, v78
	v_log_f32_e32 v76, v76
	s_nop 0
	v_mul_f32_e32 v78, 0x3f317217, v76
	v_fma_f32 v78, v76, s81, -v78
	v_fmac_f32_e32 v78, 0x3377d1cf, v76
	v_fmac_f32_e32 v78, 0x3f317217, v76
	v_cmp_lt_f32_e64 s[44:45], |v76|, s71
	s_nop 1
	v_cndmask_b32_e64 v76, v76, v78, s[44:45]
	v_cndmask_b32_e64 v78, 0, v236, s[42:43]
	v_sub_f32_e32 v76, v76, v78
	v_sub_f32_e32 v76, v77, v76
	v_fmamk_f32 v149, v76, 0x3d800000, v147
	v_lshl_add_u64 v[76:77], v[12:13], 0, s[4:5]
	v_mov_b32_e32 v78, v237
	s_lshl_b32 s4, s16, 6
	s_add_i32 s4, s4, 0x10000
	v_mov_b32_e32 v86, s4
	s_lshl_b64 s[4:5], s[6:7], 12
	s_waitcnt vmcnt(0)
	v_lshlrev_b32_e32 v150, 16, v78
	ds_read_b128 v[78:81], v86
	ds_read_b128 v[82:85], v86 offset:16
	ds_read_b128 v[152:155], v86 offset:32
	ds_read_b128 v[156:159], v86 offset:48
	s_waitcnt lgkmcnt(3)
	v_fma_f32 v86, v133, v78, v134
	v_fmac_f32_e32 v86, v126, v79
	v_fmac_f32_e32 v86, v127, v80
	v_fmac_f32_e32 v86, v128, v81
	s_waitcnt lgkmcnt(2)
	v_fmac_f32_e32 v86, v129, v82
	v_fmac_f32_e32 v86, v130, v83
	v_fmac_f32_e32 v86, v131, v84
	v_fmac_f32_e32 v86, v132, v85
	s_waitcnt lgkmcnt(1)
	v_fmac_f32_e32 v86, v0, v152
	v_fmac_f32_e32 v86, v1, v153
	v_pk_mul_f32 v[78:79], v[2:3], v[154:155]
	s_nop 0
	v_add_f32_e32 v78, v86, v78
	v_add_f32_e32 v80, v78, v79
	s_waitcnt lgkmcnt(0)
	v_pk_mul_f32 v[78:79], v[4:5], v[156:157]
	s_nop 0
	v_add_f32_e32 v78, v80, v78
	v_add_f32_e32 v80, v78, v79
	v_pk_mul_f32 v[78:79], v[6:7], v[158:159]
	s_nop 0
	v_add_f32_e32 v78, v80, v78
	v_add_f32_e32 v78, v78, v79
	v_min_f32_e32 v79, 0, v78
	v_mul_f32_e64 v78, |v78|, s65
	v_exp_f32_e32 v78, v78
	s_nop 0
	v_add_f32_e32 v78, 1.0, v78
	v_cmp_gt_f32_e64 s[42:43], s80, v78
	s_nop 1
	v_cndmask_b32_e64 v80, 0, 32, s[42:43]
	v_ldexp_f32 v78, v78, v80
	v_log_f32_e32 v78, v78
	s_nop 0
	v_mul_f32_e32 v80, 0x3f317217, v78
	v_fma_f32 v80, v78, s81, -v80
	v_fmac_f32_e32 v80, 0x3377d1cf, v78
	v_fmac_f32_e32 v80, 0x3f317217, v78
	v_cmp_lt_f32_e64 s[44:45], |v78|, s71
	s_nop 1
	v_cndmask_b32_e64 v78, v78, v80, s[44:45]
	v_cndmask_b32_e64 v80, 0, v236, s[42:43]
	v_sub_f32_e32 v78, v78, v80
	v_sub_f32_e32 v78, v79, v78
	v_fmamk_f32 v151, v78, 0x3d800000, v149
	v_lshl_add_u64 v[78:79], v[12:13], 0, s[4:5]
	v_mov_b32_e32 v80, v238
	s_lshl_b32 s4, s17, 6
	s_add_i32 s4, s4, 0x10000
	v_mov_b32_e32 v135, s4
	s_lshl_b64 s[4:5], s[54:55], 12
	s_waitcnt vmcnt(0)
	v_lshlrev_b32_e32 v152, 16, v80
	ds_read_b128 v[80:83], v135
	ds_read_b128 v[84:87], v135 offset:16
	ds_read_b128 v[154:157], v135 offset:32
	ds_read_b128 v[162:165], v135 offset:48
	s_waitcnt lgkmcnt(3)
	v_fma_f32 v135, v133, v80, v134
	v_fmac_f32_e32 v135, v126, v81
	v_fmac_f32_e32 v135, v127, v82
	v_fmac_f32_e32 v135, v128, v83
	s_waitcnt lgkmcnt(2)
	v_fmac_f32_e32 v135, v129, v84
	v_fmac_f32_e32 v135, v130, v85
	v_fmac_f32_e32 v135, v131, v86
	v_fmac_f32_e32 v135, v132, v87
	s_waitcnt lgkmcnt(1)
	v_fmac_f32_e32 v135, v0, v154
	v_fmac_f32_e32 v135, v1, v155
	v_pk_mul_f32 v[80:81], v[2:3], v[156:157]
	s_nop 0
	v_add_f32_e32 v80, v135, v80
	v_add_f32_e32 v82, v80, v81
	s_waitcnt lgkmcnt(0)
	v_pk_mul_f32 v[80:81], v[4:5], v[162:163]
	s_nop 0
	v_add_f32_e32 v80, v82, v80
	v_add_f32_e32 v82, v80, v81
	v_pk_mul_f32 v[80:81], v[6:7], v[164:165]
	s_nop 0
	v_add_f32_e32 v80, v82, v80
	v_add_f32_e32 v80, v80, v81
	v_min_f32_e32 v81, 0, v80
	v_mul_f32_e64 v80, |v80|, s65
	v_exp_f32_e32 v80, v80
	s_nop 0
	v_add_f32_e32 v80, 1.0, v80
	v_cmp_gt_f32_e64 s[42:43], s80, v80
	s_nop 1
	v_cndmask_b32_e64 v82, 0, 32, s[42:43]
	v_ldexp_f32 v80, v80, v82
	v_log_f32_e32 v80, v80
	s_nop 0
	v_mul_f32_e32 v82, 0x3f317217, v80
	v_fma_f32 v82, v80, s81, -v82
	v_fmac_f32_e32 v82, 0x3377d1cf, v80
	v_fmac_f32_e32 v82, 0x3f317217, v80
	v_cmp_lt_f32_e64 s[44:45], |v80|, s71
	s_nop 1
	v_cndmask_b32_e64 v80, v80, v82, s[44:45]
	v_cndmask_b32_e64 v82, 0, v236, s[42:43]
	v_sub_f32_e32 v80, v80, v82
	v_sub_f32_e32 v80, v81, v80
	v_fmamk_f32 v153, v80, 0x3d800000, v151
	v_lshl_add_u64 v[80:81], v[12:13], 0, s[4:5]
	v_mov_b32_e32 v82, v239
	s_lshl_b32 s4, s18, 6
	s_add_i32 s4, s4, 0x10000
	v_mov_b32_e32 v86, s4
	s_lshl_b64 s[4:5], s[48:49], 12
	s_waitcnt vmcnt(0)
	v_lshlrev_b32_e32 v154, 16, v82
	ds_read_b128 v[82:85], v86
	ds_read_b128 v[156:159], v86 offset:16
	ds_read_b128 v[162:165], v86 offset:32
	ds_read_b128 v[166:169], v86 offset:48
	s_waitcnt lgkmcnt(3)
	v_fma_f32 v86, v133, v82, v134
	v_fmac_f32_e32 v86, v126, v83
	v_fmac_f32_e32 v86, v127, v84
	v_fmac_f32_e32 v86, v128, v85
	s_waitcnt lgkmcnt(2)
	v_fmac_f32_e32 v86, v129, v156
	v_fmac_f32_e32 v86, v130, v157
	v_fmac_f32_e32 v86, v131, v158
	v_fmac_f32_e32 v86, v132, v159
	s_waitcnt lgkmcnt(1)
	v_fmac_f32_e32 v86, v0, v162
	v_fmac_f32_e32 v86, v1, v163
	v_pk_mul_f32 v[82:83], v[2:3], v[164:165]
	s_nop 0
	v_add_f32_e32 v82, v86, v82
	v_add_f32_e32 v84, v82, v83
	s_waitcnt lgkmcnt(0)
	v_pk_mul_f32 v[82:83], v[4:5], v[166:167]
	s_nop 0
	v_add_f32_e32 v82, v84, v82
	v_add_f32_e32 v84, v82, v83
	v_pk_mul_f32 v[82:83], v[6:7], v[168:169]
	s_nop 0
	v_add_f32_e32 v82, v84, v82
	v_add_f32_e32 v82, v82, v83
	v_min_f32_e32 v83, 0, v82
	v_mul_f32_e64 v82, |v82|, s65
	v_exp_f32_e32 v82, v82
	s_nop 0
	v_add_f32_e32 v82, 1.0, v82
	v_cmp_gt_f32_e64 s[42:43], s80, v82
	s_nop 1
	v_cndmask_b32_e64 v84, 0, 32, s[42:43]
	v_ldexp_f32 v82, v82, v84
	v_log_f32_e32 v82, v82
	s_nop 0
	v_mul_f32_e32 v84, 0x3f317217, v82
	v_fma_f32 v84, v82, s81, -v84
	v_fmac_f32_e32 v84, 0x3377d1cf, v82
	v_fmac_f32_e32 v84, 0x3f317217, v82
	v_cmp_lt_f32_e64 s[44:45], |v82|, s71
	s_nop 1
	v_cndmask_b32_e64 v82, v82, v84, s[44:45]
	v_cndmask_b32_e64 v84, 0, v236, s[42:43]
	v_sub_f32_e32 v82, v82, v84
	v_sub_f32_e32 v82, v83, v82
	v_fmamk_f32 v155, v82, 0x3d800000, v153
	v_lshl_add_u64 v[82:83], v[12:13], 0, s[4:5]
	v_mov_b32_e32 v84, v240
	s_lshl_b32 s4, s19, 6
	s_add_i32 s4, s4, 0x10000
	v_mov_b32_e32 v135, s4
	s_or_b32 s4, s19, s72
	s_ashr_i32 s5, s4, 31
	s_waitcnt vmcnt(0)
	v_lshlrev_b32_e32 v156, 16, v84
	ds_read_b128 v[84:87], v135
	ds_read_b128 v[162:165], v135 offset:16
	ds_read_b128 v[166:169], v135 offset:32
	ds_read_b128 v[170:173], v135 offset:48
	s_waitcnt lgkmcnt(3)
	v_fma_f32 v135, v133, v84, v134
	v_fmac_f32_e32 v135, v126, v85
	v_fmac_f32_e32 v135, v127, v86
	v_fmac_f32_e32 v135, v128, v87
	s_waitcnt lgkmcnt(2)
	v_fmac_f32_e32 v135, v129, v162
	v_fmac_f32_e32 v135, v130, v163
	v_fmac_f32_e32 v135, v131, v164
	v_fmac_f32_e32 v135, v132, v165
	s_waitcnt lgkmcnt(1)
	v_pk_mul_f32 v[84:85], v[0:1], v[166:167]
	s_nop 0
	v_add_f32_e32 v84, v135, v84
	v_add_f32_e32 v86, v84, v85
	v_pk_mul_f32 v[84:85], v[2:3], v[168:169]
	s_nop 0
	v_add_f32_e32 v84, v86, v84
	v_add_f32_e32 v86, v84, v85
	s_waitcnt lgkmcnt(0)
	v_pk_mul_f32 v[84:85], v[4:5], v[170:171]
	s_nop 0
	v_add_f32_e32 v84, v86, v84
	v_add_f32_e32 v86, v84, v85
	v_pk_mul_f32 v[84:85], v[6:7], v[172:173]
	s_nop 0
	v_add_f32_e32 v84, v86, v84
	v_add_f32_e32 v84, v84, v85
	v_min_f32_e32 v85, 0, v84
	v_mul_f32_e64 v84, |v84|, s65
	v_exp_f32_e32 v84, v84
	s_nop 0
	v_add_f32_e32 v84, 1.0, v84
	v_cmp_gt_f32_e64 s[42:43], s80, v84
	s_nop 1
	v_cndmask_b32_e64 v86, 0, 32, s[42:43]
	v_ldexp_f32 v84, v84, v86
	v_log_f32_e32 v84, v84
	s_nop 0
	v_mul_f32_e32 v86, 0x3f317217, v84
	v_fma_f32 v86, v84, s81, -v86
	v_fmac_f32_e32 v86, 0x3377d1cf, v84
	v_fmac_f32_e32 v86, 0x3f317217, v84
	v_cmp_lt_f32_e64 s[44:45], |v84|, s71
	s_nop 1
	v_cndmask_b32_e64 v84, v84, v86, s[44:45]
	v_cndmask_b32_e64 v86, 0, v236, s[42:43]
	v_sub_f32_e32 v84, v84, v86
	v_sub_f32_e32 v84, v85, v84
	s_lshl_b64 s[42:43], s[4:5], 12
	v_fmamk_f32 v157, v84, 0x3d800000, v155
	v_lshl_add_u64 v[84:85], v[12:13], 0, s[42:43]
	v_mov_b32_e32 v86, v241
	s_waitcnt vmcnt(0)
	v_lshlrev_b32_e32 v158, 16, v86
	v_mov_b32_e32 v86, s21
	ds_read_b128 v[162:165], v86
	ds_read_b128 v[166:169], v86 offset:16
	ds_read_b128 v[170:173], v86 offset:32
	ds_read_b128 v[174:177], v86 offset:48
	s_waitcnt lgkmcnt(3)
	v_fma_f32 v135, v133, v162, v134
	v_fmac_f32_e32 v135, v126, v163
	v_fmac_f32_e32 v135, v127, v164
	v_fmac_f32_e32 v135, v128, v165
	s_waitcnt lgkmcnt(2)
	v_fmac_f32_e32 v135, v129, v166
	v_fmac_f32_e32 v135, v130, v167
	v_fmac_f32_e32 v135, v131, v168
	v_fmac_f32_e32 v135, v132, v169
	s_waitcnt lgkmcnt(1)
	v_pk_mul_f32 v[86:87], v[0:1], v[170:171]
	s_nop 0
	v_add_f32_e32 v86, v135, v86
	v_add_f32_e32 v135, v86, v87
	v_pk_mul_f32 v[86:87], v[2:3], v[172:173]
	v_lshl_add_u32 v173, s3, 13, v93
	v_add_f32_e32 v86, v135, v86
	v_add_f32_e32 v135, v86, v87
	s_waitcnt lgkmcnt(0)
	v_pk_mul_f32 v[86:87], v[4:5], v[174:175]
	s_nop 0
	v_add_f32_e32 v86, v135, v86
	v_add_f32_e32 v135, v86, v87
	v_pk_mul_f32 v[86:87], v[6:7], v[176:177]
	s_nop 0
	v_add_f32_e32 v86, v135, v86
	v_add_f32_e32 v86, v86, v87
	v_min_f32_e32 v87, 0, v86
	v_mul_f32_e64 v86, |v86|, s65
	v_exp_f32_e32 v86, v86
	s_nop 0
	v_add_f32_e32 v86, 1.0, v86
	v_cmp_gt_f32_e64 s[42:43], s80, v86
	s_nop 1
	v_cndmask_b32_e64 v135, 0, 32, s[42:43]
	v_ldexp_f32 v86, v86, v135
	v_log_f32_e32 v86, v86
	s_nop 0
	v_mul_f32_e32 v135, 0x3f317217, v86
	v_fma_f32 v135, v86, s81, -v135
	v_fmac_f32_e32 v135, 0x3377d1cf, v86
	v_fmac_f32_e32 v135, 0x3f317217, v86
	v_cmp_lt_f32_e64 s[44:45], |v86|, s71
	s_nop 1
	v_cndmask_b32_e64 v86, v86, v135, s[44:45]
	v_cndmask_b32_e64 v135, 0, v236, s[42:43]
	s_or_b32 s42, s20, s72
	v_sub_f32_e32 v86, v86, v135
	s_ashr_i32 s43, s42, 31
	v_sub_f32_e32 v86, v87, v86
	s_lshl_b64 s[44:45], s[42:43], 12
	v_fmamk_f32 v135, v86, 0x3d800000, v157
	v_lshl_add_u64 v[86:87], v[12:13], 0, s[44:45]
	v_mov_b32_e32 v159, v221
	global_load_ushort v174, v[60:61], off offset:2048
	global_load_ushort v176, v[14:15], off offset:2048
	global_load_ushort v175, v[56:57], off offset:2048
	global_load_ushort v177, v[62:63], off offset:2048
	global_load_ushort v169, v[64:65], off offset:2048
	global_load_ushort v171, v[68:69], off offset:2048
	global_load_ushort v170, v[66:67], off offset:2048
	global_load_ushort v172, v[70:71], off offset:2048
	global_load_ushort v165, v[72:73], off offset:2048
	global_load_ushort v167, v[76:77], off offset:2048
	global_load_ushort v166, v[74:75], off offset:2048
	global_load_ushort v168, v[78:79], off offset:2048
	global_load_ushort v161, v[80:81], off offset:2048
	global_load_ushort v163, v[84:85], off offset:2048
	global_load_ushort v162, v[82:83], off offset:2048
	global_load_ushort v164, v[86:87], off offset:2048
	s_lshl_b64 s[44:45], s[50:51], 11
	v_lshl_add_u64 v[14:15], v[8:9], 0, s[44:45]
	v_mul_f32_e32 v15, 0x3fb8aa3b, v59
	v_exp_f32_e32 v15, v15
	v_mul_f32_e32 v14, 0x3d800000, v88
	s_lshl_b64 s[44:45], s[74:75], 11
	v_lshl_add_u64 v[56:57], v[8:9], 0, s[44:45]
	v_mul_f32_e32 v15, v14, v15
	v_cvt_pk_bf16_f32 v178, v15, s0
	v_mul_f32_e32 v56, 0x3fb8aa3b, v89
	v_exp_f32_e32 v56, v56
	v_mul_f32_e32 v15, 0x3d800000, v90
	s_lshl_b64 s[44:45], s[76:77], 11
	v_mul_f32_e32 v14, 0xbfb8aa3b, v59
	v_mul_f32_e32 v15, v15, v56
	v_mul_f32_e32 v56, 0xbfb8aa3b, v89
	v_exp_f32_e32 v59, v56
	v_cvt_pk_bf16_f32 v180, v15, s0
	v_lshl_add_u64 v[56:57], v[8:9], 0, s[44:45]
	v_mul_f32_e32 v56, 0x3fb8aa3b, v91
	v_exp_f32_e32 v56, v56
	v_mul_f32_e32 v15, 0x3d800000, v136
	s_lshl_b64 s[44:45], s[82:83], 11
	v_mul_f32_e32 v62, 0x3fb8aa3b, v143
	v_mul_f32_e32 v56, v15, v56
	v_cvt_pk_bf16_f32 v182, v56, s0
	v_lshl_add_u64 v[56:57], v[8:9], 0, s[44:45]
	v_mul_f32_e32 v57, 0x3fb8aa3b, v137
	v_exp_f32_e32 v57, v57
	v_mul_f32_e32 v56, 0x3d800000, v138
	s_lshl_b64 s[44:45], s[96:97], 11
	v_lshl_add_u64 v[60:61], v[8:9], 0, s[44:45]
	v_mul_f32_e32 v57, v56, v57
	v_cvt_pk_bf16_f32 v183, v57, s0
	v_mul_f32_e32 v60, 0x3fb8aa3b, v139
	v_exp_f32_e32 v60, v60
	v_mul_f32_e32 v61, 0x3fb8aa3b, v141
	v_exp_f32_e32 v61, v61
	v_mul_f32_e32 v57, 0x3d800000, v140
	v_mul_f32_e32 v57, v57, v60
	v_exp_f32_e32 v62, v62
	v_cvt_pk_bf16_f32 v138, v57, s0
	v_mul_f32_e32 v57, 0x3d800000, v142
	v_mul_f32_e32 v63, 0x3fb8aa3b, v145
	v_mul_f32_e32 v61, v57, v61
	v_exp_f32_e32 v63, v63
	v_mul_f32_e32 v57, 0xbfb8aa3b, v141
	v_cvt_pk_bf16_f32 v141, v61, s0
	v_mul_f32_e32 v61, 0x3d800000, v144
	v_mul_f32_e32 v64, 0x3fb8aa3b, v147
	v_mul_f32_e32 v15, 0xbfb8aa3b, v91
	v_mul_f32_e32 v62, v61, v62
	v_exp_f32_e32 v64, v64
	v_exp_f32_e32 v14, v14
	v_exp_f32_e32 v15, v15
	v_cvt_pk_bf16_f32 v186, v62, s0
	v_mul_f32_e32 v62, 0x3d800000, v146
	v_mul_f32_e32 v65, 0x3fb8aa3b, v149
	v_mul_f32_e32 v63, v62, v63
	v_exp_f32_e32 v65, v65
	v_cvt_pk_bf16_f32 v193, v63, s0
	v_mul_f32_e32 v63, 0x3d800000, v148
	v_mul_f32_e32 v68, 0x3fb8aa3b, v151
	v_mul_f32_e32 v63, v63, v64
	v_exp_f32_e32 v68, v68
	s_waitcnt vmcnt(14)
	v_lshlrev_b32_e32 v194, 16, v176
	v_lshlrev_b32_e32 v195, 16, v174
	s_waitcnt vmcnt(12)
	v_lshlrev_b32_e32 v177, 16, v177
	v_lshlrev_b32_e32 v176, 16, v175
	v_mul_f32_e32 v56, 0xbfb8aa3b, v137
	v_mul_f32_e32 v61, 0xbfb8aa3b, v143
	v_cvt_pk_bf16_f32 v143, v63, s0
	v_mul_f32_e32 v63, 0x3d800000, v150
	v_mul_f32_e32 v69, 0x3fb8aa3b, v153
	v_pk_mul_f32 v[58:59], v[58:59], v[194:195]
	v_pk_mul_f32 v[14:15], v[14:15], v[176:177]
	v_exp_f32_e32 v56, v56
	v_mul_f32_e32 v60, 0xbfb8aa3b, v139
	v_exp_f32_e32 v57, v57
	v_mul_f32_e32 v65, v63, v65
	v_exp_f32_e32 v69, v69
	v_cvt_pk_bf16_f32 v58, v58, v59
	v_cvt_pk_bf16_f32 v14, v14, v15
	ds_write_b16 v173, v160
	v_lshl_add_u32 v160, s66, 9, v111
	v_exp_f32_e32 v60, v60
	v_lshl_add_u64 v[66:67], v[8:9], 0, s[8:9]
	s_lshl_b64 s[8:9], s[46:47], 11
	v_exp_f32_e32 v61, v61
	v_cvt_pk_bf16_f32 v146, v65, s0
	v_mul_f32_e32 v65, 0x3d800000, v152
	v_mul_f32_e32 v72, 0x3fb8aa3b, v155
	v_lshrrev_b32_e32 v15, 16, v58
	v_lshrrev_b32_e32 v59, 16, v14
	v_lshl_add_u64 v[70:71], v[8:9], 0, s[8:9]
	s_lshl_b64 s[8:9], s[60:61], 11
	s_lshl_b64 s[0:1], s[0:1], 11
	v_mul_f32_e32 v68, v65, v68
	v_exp_f32_e32 v72, v72
	ds_write_b16 v173, v58 offset:32768
	ds_write_b16 v160, v178
	ds_write_b16 v160, v14 offset:32768
	ds_write_b16 v179, v180
	ds_write_b16 v179, v15 offset:32768
	ds_write_b16 v181, v182
	ds_write_b16 v181, v59 offset:32768
	v_and_b32_e32 v59, 0xffff0000, v14
	v_lshlrev_b32_e32 v14, 16, v14
	v_lshl_add_u32 v137, s69, 9, v114
	v_lshl_add_u64 v[76:77], v[8:9], 0, s[8:9]
	s_lshl_b64 s[8:9], s[62:63], 11
	v_cvt_pk_bf16_f32 v150, v68, s0
	v_mul_f32_e32 v68, 0x3d800000, v154
	v_mul_f32_e32 v73, 0x3fb8aa3b, v157
	v_or_b32_e32 v59, v59, v15
	v_or_b32_sdwa v58, v14, v58 dst_sel:DWORD dst_unused:UNUSED_PAD src0_sel:DWORD src1_sel:WORD_0
	s_waitcnt vmcnt(10)
	v_lshlrev_b32_e32 v15, 16, v171
	v_lshlrev_b32_e32 v14, 16, v169
	v_mul_f32_e32 v62, 0xbfb8aa3b, v145
	v_lshl_add_u64 v[80:81], v[8:9], 0, s[8:9]
	v_mul_f32_e32 v63, 0xbfb8aa3b, v149
	v_lshl_add_u64 v[78:79], v[8:9], 0, s[0:1]
	s_lshl_b64 s[0:1], s[6:7], 11
	v_mul_f32_e32 v69, v68, v69
	v_exp_f32_e32 v73, v73
	ds_write_b16 v137, v183
	s_waitcnt vmcnt(8)
	v_lshlrev_b32_e32 v67, 16, v172
	v_lshlrev_b32_e32 v66, 16, v170
	v_pk_mul_f32 v[14:15], v[56:57], v[14:15]
	v_exp_f32_e32 v62, v62
	v_mul_f32_e32 v64, 0xbfb8aa3b, v147
	v_exp_f32_e32 v63, v63
	v_mul_f32_e32 v65, 0xbfb8aa3b, v151
	v_cvt_pk_bf16_f32 v154, v69, s0
	v_mul_f32_e32 v69, 0x3d800000, v156
	v_mul_f32_e32 v90, 0x3fb8aa3b, v135
	v_cvt_pk_bf16_f32 v56, v14, v15
	v_pk_mul_f32 v[14:15], v[60:61], v[66:67]
	v_exp_f32_e32 v64, v64
	v_exp_f32_e32 v65, v65
	v_lshl_add_u64 v[84:85], v[8:9], 0, s[0:1]
	s_lshl_b64 s[0:1], s[54:55], 11
	v_mul_f32_e32 v69, v69, v72
	v_exp_f32_e32 v136, v90
	v_cvt_pk_bf16_f32 v14, v14, v15
	v_cvt_pk_bf16_f32 v148, v69, s0
	v_mul_f32_e32 v69, 0x3d800000, v158
	v_lshrrev_b32_e32 v15, 16, v14
	v_lshlrev_b32_e32 v159, 16, v159
	v_lshl_add_u32 v139, s10, 9, v115
	v_lshl_add_u32 v142, s11, 9, v116
	v_lshl_add_u32 v140, s13, 9, v118
	v_lshl_add_u64 v[88:89], v[8:9], 0, s[0:1]
	s_lshl_b64 s[0:1], s[48:49], 11
	v_mul_f32_e32 v73, v69, v73
	v_lshrrev_b32_e32 v57, 16, v56
	v_and_b32_e32 v60, 0xffff0000, v14
	v_lshlrev_b32_e32 v66, 16, v14
	ds_write_b16 v137, v56 offset:32768
	ds_write_b16 v139, v138
	ds_write_b16 v139, v14 offset:32768
	ds_write_b16 v142, v141
	ds_write_b16 v142, v57 offset:32768
	ds_write_b16 v192, v186
	ds_write_b16 v192, v15 offset:32768
	ds_write_b16 v140, v193
	s_waitcnt vmcnt(6)
	v_lshlrev_b32_e32 v15, 16, v167
	v_lshlrev_b32_e32 v14, 16, v165
	v_mul_f32_e32 v68, 0xbfb8aa3b, v153
	v_mul_f32_e32 v69, 0xbfb8aa3b, v157
	v_cvt_pk_bf16_f32 v152, v73, s0
	v_mul_f32_e32 v73, 0x3d800000, v159
	v_or_b32_e32 v61, v60, v57
	v_or_b32_sdwa v60, v66, v56 dst_sel:DWORD dst_unused:UNUSED_PAD src0_sel:DWORD src1_sel:WORD_0
	s_waitcnt vmcnt(4)
	v_lshlrev_b32_e32 v57, 16, v168
	v_lshlrev_b32_e32 v56, 16, v166
	v_pk_mul_f32 v[14:15], v[62:63], v[14:15]
	v_exp_f32_e32 v68, v68
	v_mul_f32_e32 v72, 0xbfb8aa3b, v155
	v_exp_f32_e32 v69, v69
	v_mul_f32_e32 v90, v73, v136
	v_mul_f32_e32 v73, 0xbfb8aa3b, v135
	v_cvt_pk_bf16_f32 v62, v14, v15
	v_pk_mul_f32 v[14:15], v[64:65], v[56:57]
	s_lshl_b64 s[8:9], s[56:57], 11
	v_exp_f32_e32 v72, v72
	v_exp_f32_e32 v73, v73
	v_cvt_pk_bf16_f32 v14, v14, v15
	v_lshl_add_u64 v[74:75], v[8:9], 0, s[8:9]
	v_lshl_add_u64 v[82:83], v[8:9], 0, s[0:1]
	s_lshl_b64 s[0:1], s[4:5], 11
	v_lshrrev_b32_e32 v15, 16, v14
	v_lshl_add_u32 v144, s14, 9, v119
	v_lshl_add_u32 v147, s15, 9, v120
	v_lshl_add_u32 v151, s16, 9, v121
	v_lshl_add_u32 v145, s17, 9, v122
	v_lshl_add_u64 v[86:87], v[8:9], 0, s[0:1]
	v_cvt_pk_bf16_f32 v155, v90, s0
	s_lshl_b64 s[0:1], s[42:43], 11
	s_lshl_b32 s66, s3, 10
	v_lshrrev_b32_e32 v63, 16, v62
	v_and_b32_e32 v56, 0xffff0000, v14
	v_lshlrev_b32_e32 v64, 16, v14
	ds_write_b16 v140, v62 offset:32768
	ds_write_b16 v144, v143
	ds_write_b16 v144, v14 offset:32768
	ds_write_b16 v147, v146
	ds_write_b16 v147, v63 offset:32768
	ds_write_b16 v151, v150
	ds_write_b16 v151, v15 offset:32768
	ds_write_b16 v145, v154
	s_waitcnt vmcnt(2)
	v_lshlrev_b32_e32 v15, 16, v163
	v_lshlrev_b32_e32 v14, 16, v161
	v_lshl_add_u64 v[90:91], v[8:9], 0, s[0:1]
	v_lshl_add_u64 v[158:159], v[10:11], 0, s[66:67]
	global_store_dwordx4 v[158:159], v[58:61], off
	v_pk_mul_f32 v[14:15], v[68:69], v[14:15]
	v_or_b32_e32 v57, v56, v63
	s_waitcnt vmcnt(1)
	v_lshlrev_b32_e32 v59, 16, v164
	v_lshlrev_b32_e32 v58, 16, v162
	v_cvt_pk_bf16_f32 v60, v14, v15
	v_pk_mul_f32 v[14:15], v[72:73], v[58:59]
	v_or_b32_sdwa v56, v64, v62 dst_sel:DWORD dst_unused:UNUSED_PAD src0_sel:DWORD src1_sel:WORD_0
	v_cvt_pk_bf16_f32 v14, v14, v15
	v_lshrrev_b32_e32 v61, 16, v60
	v_and_b32_e32 v58, 0xffff0000, v14
	v_lshlrev_b32_e32 v62, 16, v14
	v_or_b32_e32 v59, v58, v61
	v_or_b32_sdwa v58, v62, v60 dst_sel:DWORD dst_unused:UNUSED_PAD src0_sel:DWORD src1_sel:WORD_0
	s_add_i32 s3, s3, 1
	v_lshl_add_u32 v149, s18, 9, v123
	v_lshl_add_u32 v153, s19, 9, v124
	v_lshl_add_u32 v156, s20, 9, v125
	v_lshrrev_b32_e32 v15, 16, v14
	ds_write_b16 v145, v60 offset:32768
	ds_write_b16 v149, v148
	ds_write_b16 v149, v14 offset:32768
	ds_write_b16 v153, v152
	ds_write_b16 v153, v61 offset:32768
	ds_write_b16 v156, v155
	ds_write_b16 v156, v15 offset:32768
	global_store_dwordx4 v[158:159], v[56:59], off offset:512
	s_cmp_eq_u32 s3, 4
	s_nop 0
	v_mov_b32_e32 v58, v135
	s_cbranch_scc0 .LBB0_224
	s_ashr_i32 s3, s2, 31
	s_lshl_b64 s[0:1], s[2:3], 10
	v_lshl_add_u64 v[0:1], v[22:23], 0, s[0:1]
	global_store_dword v[0:1], v136, off
	v_mov_b32_e32 v0, 0
	v_mov_b32_e32 v1, 0
	v_mov_b32_e32 v2, 0
	v_mov_b32_e32 v3, 0
	v_mov_b32_e32 v4, 0
	v_mov_b32_e32 v5, 0
	v_mov_b32_e32 v6, 0
	v_mov_b32_e32 v7, 0
	v_mov_b32_e32 v8, 0
	v_mov_b32_e32 v9, 0
	v_mov_b32_e32 v10, 0
	v_mov_b32_e32 v11, 0
	v_mov_b32_e32 v12, 0
	v_mov_b32_e32 v13, 0
	v_mov_b32_e32 v14, 0
	v_mov_b32_e32 v15, 0
	s_waitcnt lgkmcnt(0)
	s_barrier
	s_and_b32 s4, s2, 3
	s_lshl_b32 s4, s4, 22
	s_lshr_b32 s5, s2, 2
	s_lshl_b32 s5, s5, 15
	s_or_b32 s4, s4, s5
	s_add_u32 s4, s4, 0xe800000
	v_lshlrev_b32_e32 v196, 4, v16
	v_mov_b32_e32 v197, 0
	v_add_u32_e32 v196, s4, v196
	v_lshl_add_u64 v[196:197], v[184:185], 0, v[196:197]
	v_and_b32_e32 v198, 31, v16
	v_bfe_u32 v199, v16, 5, 1
	v_lshrrev_b32_e32 v200, 6, v16
	v_lshlrev_b32_e32 v201, 9, v198
	v_lshl_add_u32 v201, v199, 3, v201
	v_and_b32_e32 v202, 15, v198
	v_lshlrev_b32_e32 v200, 1, v200
	v_xor_b32_e32 v203, v200, v202
	v_lshl_add_u32 v203, v203, 4, v201
	v_xor_b32_e32 v204, 16, v203
	ds_read_b64 v[208:209], v203
	ds_read_b64 v[210:211], v204
	s_waitcnt lgkmcnt(0)
	global_store_dwordx4 v[196:197], v[208:211], off
	v_lshl_add_u64 v[196:197], v[196:197], 0, s[86:87]
	ds_read_b64 v[212:213], v203 offset:16384
	ds_read_b64 v[214:215], v204 offset:16384
	s_waitcnt lgkmcnt(0)
	global_store_dwordx4 v[196:197], v[212:215], off
	v_lshl_add_u64 v[196:197], v[196:197], 0, s[86:87]
	v_add_u32_e32 v205, 8, v200
	v_xor_b32_e32 v203, v205, v202
	v_lshl_add_u32 v203, v203, 4, v201
	v_xor_b32_e32 v204, 16, v203
	ds_read_b64 v[208:209], v203
	ds_read_b64 v[210:211], v204
	s_waitcnt lgkmcnt(0)
	global_store_dwordx4 v[196:197], v[208:211], off
	v_lshl_add_u64 v[196:197], v[196:197], 0, s[86:87]
	ds_read_b64 v[212:213], v203 offset:16384
	ds_read_b64 v[214:215], v204 offset:16384
	s_waitcnt lgkmcnt(0)
	global_store_dwordx4 v[196:197], v[212:215], off
	v_lshl_add_u64 v[196:197], v[196:197], 0, s[86:87]
	v_add_u32_e32 v205, 16, v200
	v_xor_b32_e32 v203, v205, v202
	v_lshl_add_u32 v203, v203, 4, v201
	v_xor_b32_e32 v204, 16, v203
	ds_read_b64 v[208:209], v203
	ds_read_b64 v[210:211], v204
	s_waitcnt lgkmcnt(0)
	global_store_dwordx4 v[196:197], v[208:211], off
	v_lshl_add_u64 v[196:197], v[196:197], 0, s[86:87]
	ds_read_b64 v[212:213], v203 offset:16384
	ds_read_b64 v[214:215], v204 offset:16384
	s_waitcnt lgkmcnt(0)
	global_store_dwordx4 v[196:197], v[212:215], off
	v_lshl_add_u64 v[196:197], v[196:197], 0, s[86:87]
	v_add_u32_e32 v205, 24, v200
	v_xor_b32_e32 v203, v205, v202
	v_lshl_add_u32 v203, v203, 4, v201
	v_xor_b32_e32 v204, 16, v203
	ds_read_b64 v[208:209], v203
	ds_read_b64 v[210:211], v204
	s_waitcnt lgkmcnt(0)
	global_store_dwordx4 v[196:197], v[208:211], off
	v_lshl_add_u64 v[196:197], v[196:197], 0, s[86:87]
	ds_read_b64 v[212:213], v203 offset:16384
	ds_read_b64 v[214:215], v204 offset:16384
	s_waitcnt lgkmcnt(0)
	global_store_dwordx4 v[196:197], v[212:215], off
	s_mov_b64 s[0:1], exec
	v_readlane_b32 s4, v255, 19
	v_readlane_b32 s5, v255, 20
	s_and_b64 s[4:5], s[0:1], s[4:5]
	s_mov_b64 exec, s[4:5]
	s_cbranch_execz .LBB0_222
	v_add_u32_e32 v0, v17, v95
	ds_read_b128 v[0:3], v0
	v_add_u32_e32 v4, v94, v95
	ds_read_b128 v[4:7], v4 offset:32768
	v_add_u32_e32 v56, v17, v96
	ds_read_b128 v[56:59], v56
	v_add_u32_e32 v60, v94, v96
	ds_read_b128 v[60:63], v60 offset:32768
	v_add_u32_e32 v64, v17, v97
	s_waitcnt lgkmcnt(2)
	v_mfma_f32_32x32x16_bf16 v[0:15], v[0:3], v[4:7], 0
	s_waitcnt lgkmcnt(0)
	v_mfma_f32_32x32x16_bf16 v[0:15], v[56:59], v[60:63], v[0:15]
	ds_read_b128 v[56:59], v64
	v_add_u32_e32 v60, v94, v97
	ds_read_b128 v[60:63], v60 offset:32768
	v_add_u32_e32 v64, v17, v98
	s_waitcnt lgkmcnt(0)
	v_mfma_f32_32x32x16_bf16 v[0:15], v[56:59], v[60:63], v[0:15]
	ds_read_b128 v[56:59], v64
	v_add_u32_e32 v60, v94, v98
	ds_read_b128 v[60:63], v60 offset:32768
	v_add_u32_e32 v64, v17, v99
	s_waitcnt lgkmcnt(0)
	v_mfma_f32_32x32x16_bf16 v[0:15], v[56:59], v[60:63], v[0:15]
	ds_read_b128 v[56:59], v64
	v_add_u32_e32 v60, v94, v99
	ds_read_b128 v[60:63], v60 offset:32768
	v_add_u32_e32 v64, v17, v100
	s_waitcnt lgkmcnt(0)
	v_mfma_f32_32x32x16_bf16 v[0:15], v[56:59], v[60:63], v[0:15]
	ds_read_b128 v[56:59], v64
	v_add_u32_e32 v60, v94, v100
	ds_read_b128 v[60:63], v60 offset:32768
	v_add_u32_e32 v64, v17, v101
	s_waitcnt lgkmcnt(0)
	v_mfma_f32_32x32x16_bf16 v[0:15], v[56:59], v[60:63], v[0:15]
	ds_read_b128 v[56:59], v64
	v_add_u32_e32 v60, v94, v101
	ds_read_b128 v[60:63], v60 offset:32768
	v_add_u32_e32 v64, v17, v102
	s_waitcnt lgkmcnt(0)
	v_mfma_f32_32x32x16_bf16 v[0:15], v[56:59], v[60:63], v[0:15]
	ds_read_b128 v[56:59], v64
	v_add_u32_e32 v60, v94, v102
	ds_read_b128 v[60:63], v60 offset:32768
	v_add_u32_e32 v64, v17, v103
	s_waitcnt lgkmcnt(0)
	v_mfma_f32_32x32x16_bf16 v[0:15], v[56:59], v[60:63], v[0:15]
	ds_read_b128 v[56:59], v64
	v_add_u32_e32 v60, v94, v103
	ds_read_b128 v[60:63], v60 offset:32768
	v_add_u32_e32 v64, v17, v104
	s_waitcnt lgkmcnt(0)
	v_mfma_f32_32x32x16_bf16 v[0:15], v[56:59], v[60:63], v[0:15]
	ds_read_b128 v[56:59], v64
	v_add_u32_e32 v60, v94, v104
	ds_read_b128 v[60:63], v60 offset:32768
	v_add_u32_e32 v64, v17, v105
	s_waitcnt lgkmcnt(0)
	v_mfma_f32_32x32x16_bf16 v[0:15], v[56:59], v[60:63], v[0:15]
	ds_read_b128 v[56:59], v64
	v_add_u32_e32 v60, v94, v105
	ds_read_b128 v[60:63], v60 offset:32768
	v_add_u32_e32 v64, v17, v106
	s_waitcnt lgkmcnt(0)
	v_mfma_f32_32x32x16_bf16 v[0:15], v[56:59], v[60:63], v[0:15]
	ds_read_b128 v[56:59], v64
	v_add_u32_e32 v60, v94, v106
	ds_read_b128 v[60:63], v60 offset:32768
	v_add_u32_e32 v64, v17, v107
	s_waitcnt lgkmcnt(0)
	v_mfma_f32_32x32x16_bf16 v[0:15], v[56:59], v[60:63], v[0:15]
	ds_read_b128 v[56:59], v64
	v_add_u32_e32 v60, v94, v107
	ds_read_b128 v[60:63], v60 offset:32768
	v_add_u32_e32 v64, v17, v108
	s_waitcnt lgkmcnt(0)
	v_mfma_f32_32x32x16_bf16 v[0:15], v[56:59], v[60:63], v[0:15]
	ds_read_b128 v[56:59], v64
	v_add_u32_e32 v60, v94, v108
	ds_read_b128 v[60:63], v60 offset:32768
	v_add_u32_e32 v64, v17, v109
	s_waitcnt lgkmcnt(0)
	v_mfma_f32_32x32x16_bf16 v[0:15], v[56:59], v[60:63], v[0:15]
	ds_read_b128 v[56:59], v64
	v_add_u32_e32 v60, v94, v109
	ds_read_b128 v[60:63], v60 offset:32768
	v_add_u32_e32 v64, v17, v110
	s_waitcnt lgkmcnt(0)
	v_mfma_f32_32x32x16_bf16 v[0:15], v[56:59], v[60:63], v[0:15]
	ds_read_b128 v[56:59], v64
	v_add_u32_e32 v60, v94, v110
	ds_read_b128 v[60:63], v60 offset:32768
	s_waitcnt lgkmcnt(0)
	v_mfma_f32_32x32x16_bf16 v[0:15], v[56:59], v[60:63], v[0:15]
	s_branch .LBB0_222
